# P1 w_in epilogue (kind 0): row_rstd loads batched, acc pre-scaled, serialized chains removed
# baseline (speedup 1.0000x reference)
; __device__ __forceinline__ float row_rstd(const float* ssp, int row, int fq) {
;     const f32x4 a = *(const f32x4*)(ssp + (size_t)row * 32 + 8 * fq), b = *(const f32x4*)(ssp + (size_t)row * 32 + 8 * fq + 4);
;     float s = ((a[0] + a[1]) + (a[2] + a[3])) + ((b[0] + b[1]) + (b[2] + b[3]));
;     s += __shfl_xor(s, 16); s += __shfl_xor(s, 32);
;     return __builtin_amdgcn_rsqf(s * (1.0f / 2048.0f) + 1e-6f);
; }
;     __device__ __forceinline__ void operator()(f32x4 (&acc)[2][2][4][2], const Unit& u, int wr, int wc, int fr, int fq) const {
;     ...
;             const int row0 = u.pm * BM + wr * 64 + fr, col0 = colt + wc * 64 + 8 * fq;
; #pragma unroll
;             for (int ai = 0; ai < 2; ++ai)
; #pragma unroll
;                 for (int m = 0; m < 4; ++m) {
;                     const int row = row0 + ai * HALF + m * 16;
;                     float rstd = row_rstd(ss, row, fq); if (mode == 1) rstd *= 0.125f;
.LBB0_196:
	v_lshl_add_u32 v2, s82, 8, v211
	v_lshlrev_b32_e32 v2, 7, v2
	v_mov_b32_e32 v3, 0
	v_lshl_add_u64 v[144:145], v[178:179], 0, v[2:3]
	v_add_u32_e32 v2, 0x1000, v2
	v_lshl_add_u64 v[208:209], v[178:179], 0, v[2:3]
	v_add_u32_e32 v2, 0x3000, v2
	v_lshl_add_u64 v[230:231], v[178:179], 0, v[2:3]
	v_add_u32_e32 v2, 0x1000, v2
	v_lshl_add_u64 v[238:239], v[178:179], 0, v[2:3]
	global_load_dwordx4 v[132:135], v[144:145], off
	global_load_dwordx4 v[136:139], v[144:145], off offset:16
	global_load_dwordx4 v[140:143], v[144:145], off offset:2048
	global_load_dwordx4 v[148:151], v[144:145], off offset:2064
	global_load_dwordx4 v[152:155], v[208:209], off
	global_load_dwordx4 v[184:187], v[208:209], off offset:16
	global_load_dwordx4 v[188:191], v[208:209], off offset:2048
	global_load_dwordx4 v[192:195], v[208:209], off offset:2064
	global_load_dwordx4 v[196:199], v[230:231], off
	global_load_dwordx4 v[200:203], v[230:231], off offset:16
	global_load_dwordx4 v[204:207], v[230:231], off offset:2048
	global_load_dwordx4 v[218:221], v[230:231], off offset:2064
	global_load_dwordx4 v[222:225], v[238:239], off
	global_load_dwordx4 v[226:229], v[238:239], off offset:16
	global_load_dwordx4 v[246:249], v[238:239], off offset:2048
	global_load_dwordx4 v[250:253], v[238:239], off offset:2064
	v_xor_b32_e32 v0, 16, v241
	v_xor_b32_e32 v162, 32, v241
	v_lshlrev_b32_e32 v0, 2, v0
	v_lshlrev_b32_e32 v162, 2, v162
	s_waitcnt vmcnt(14)
	v_add_f32_e32 v132, v132, v133
	v_add_f32_e32 v134, v134, v135
	v_add_f32_e32 v136, v136, v137
	v_add_f32_e32 v138, v138, v139
	v_add_f32_e32 v132, v132, v134
	v_add_f32_e32 v136, v136, v138
	v_add_f32_e32 v132, v132, v136
	s_waitcnt vmcnt(12)
	v_add_f32_e32 v140, v140, v141
	v_add_f32_e32 v142, v142, v143
	v_add_f32_e32 v148, v148, v149
	v_add_f32_e32 v150, v150, v151
	v_add_f32_e32 v140, v140, v142
	v_add_f32_e32 v148, v148, v150
	v_add_f32_e32 v140, v140, v148
	s_waitcnt vmcnt(10)
	v_add_f32_e32 v152, v152, v153
	v_add_f32_e32 v154, v154, v155
	v_add_f32_e32 v184, v184, v185
	v_add_f32_e32 v186, v186, v187
	v_add_f32_e32 v152, v152, v154
	v_add_f32_e32 v184, v184, v186
	v_add_f32_e32 v152, v152, v184
	s_waitcnt vmcnt(8)
	v_add_f32_e32 v188, v188, v189
	v_add_f32_e32 v190, v190, v191
	v_add_f32_e32 v192, v192, v193
	v_add_f32_e32 v194, v194, v195
	v_add_f32_e32 v188, v188, v190
	v_add_f32_e32 v192, v192, v194
	v_add_f32_e32 v188, v188, v192
	s_waitcnt vmcnt(6)
	v_add_f32_e32 v196, v196, v197
	v_add_f32_e32 v198, v198, v199
	v_add_f32_e32 v200, v200, v201
	v_add_f32_e32 v202, v202, v203
	v_add_f32_e32 v196, v196, v198
	v_add_f32_e32 v200, v200, v202
	v_add_f32_e32 v196, v196, v200
	s_waitcnt vmcnt(4)
	v_add_f32_e32 v204, v204, v205
	v_add_f32_e32 v206, v206, v207
	v_add_f32_e32 v218, v218, v219
	v_add_f32_e32 v220, v220, v221
	v_add_f32_e32 v204, v204, v206
	v_add_f32_e32 v218, v218, v220
	v_add_f32_e32 v204, v204, v218
	s_waitcnt vmcnt(2)
	v_add_f32_e32 v222, v222, v223
	v_add_f32_e32 v224, v224, v225
	v_add_f32_e32 v226, v226, v227
	v_add_f32_e32 v228, v228, v229
	v_add_f32_e32 v222, v222, v224
	v_add_f32_e32 v226, v226, v228
	v_add_f32_e32 v222, v222, v226
	s_waitcnt vmcnt(0)
	v_add_f32_e32 v246, v246, v247
	v_add_f32_e32 v248, v248, v249
	v_add_f32_e32 v250, v250, v251
	v_add_f32_e32 v252, v252, v253
	v_add_f32_e32 v246, v246, v248
	v_add_f32_e32 v250, v250, v252
	v_add_f32_e32 v246, v246, v250
	ds_bpermute_b32 v136, v0, v132
	ds_bpermute_b32 v148, v0, v140
	ds_bpermute_b32 v184, v0, v152
	ds_bpermute_b32 v192, v0, v188
	ds_bpermute_b32 v200, v0, v196
	ds_bpermute_b32 v218, v0, v204
	ds_bpermute_b32 v226, v0, v222
	ds_bpermute_b32 v250, v0, v246
	s_waitcnt lgkmcnt(0)
	v_add_f32_e32 v132, v132, v136
	v_add_f32_e32 v140, v140, v148
	v_add_f32_e32 v152, v152, v184
	v_add_f32_e32 v188, v188, v192
	v_add_f32_e32 v196, v196, v200
	v_add_f32_e32 v204, v204, v218
	v_add_f32_e32 v222, v222, v226
	v_add_f32_e32 v246, v246, v250
	ds_bpermute_b32 v136, v162, v132
	ds_bpermute_b32 v148, v162, v140
	ds_bpermute_b32 v184, v162, v152
	ds_bpermute_b32 v192, v162, v188
	ds_bpermute_b32 v200, v162, v196
	ds_bpermute_b32 v218, v162, v204
	ds_bpermute_b32 v226, v162, v222
	ds_bpermute_b32 v250, v162, v246
	s_waitcnt lgkmcnt(0)
	v_add_f32_e32 v132, v132, v136
	v_add_f32_e32 v140, v140, v148
	v_add_f32_e32 v152, v152, v184
	v_add_f32_e32 v188, v188, v192
	v_add_f32_e32 v196, v196, v200
	v_add_f32_e32 v204, v204, v218
	v_add_f32_e32 v222, v222, v226
	v_add_f32_e32 v246, v246, v250
	v_fmamk_f32 v132, v132, 0x3a000000, v243
	v_fmamk_f32 v140, v140, 0x3a000000, v243
	v_fmamk_f32 v152, v152, 0x3a000000, v243
	v_fmamk_f32 v188, v188, 0x3a000000, v243
	v_fmamk_f32 v196, v196, 0x3a000000, v243
	v_fmamk_f32 v204, v204, 0x3a000000, v243
	v_fmamk_f32 v222, v222, 0x3a000000, v243
	v_fmamk_f32 v246, v246, 0x3a000000, v243
	v_rsq_f32_e32 v132, v132
	v_rsq_f32_e32 v140, v140
	v_rsq_f32_e32 v152, v152
	v_rsq_f32_e32 v188, v188
	v_rsq_f32_e32 v196, v196
	v_rsq_f32_e32 v204, v204
	v_rsq_f32_e32 v222, v222
	v_rsq_f32_e32 v246, v246
	s_nop 0
	v_pk_mul_f32 v[128:129], v[128:129], v[132:133] op_sel_hi:[1,0]
	v_pk_mul_f32 v[130:131], v[130:131], v[132:133] op_sel_hi:[1,0]
	v_pk_mul_f32 v[124:125], v[124:125], v[132:133] op_sel_hi:[1,0]
	v_pk_mul_f32 v[126:127], v[126:127], v[132:133] op_sel_hi:[1,0]
	v_pk_mul_f32 v[120:121], v[120:121], v[132:133] op_sel_hi:[1,0]
	v_pk_mul_f32 v[122:123], v[122:123], v[132:133] op_sel_hi:[1,0]
	v_pk_mul_f32 v[116:117], v[116:117], v[132:133] op_sel_hi:[1,0]
	v_pk_mul_f32 v[118:119], v[118:119], v[132:133] op_sel_hi:[1,0]
	v_pk_mul_f32 v[112:113], v[112:113], v[140:141] op_sel_hi:[1,0]
	v_pk_mul_f32 v[114:115], v[114:115], v[140:141] op_sel_hi:[1,0]
; __device__ __forceinline__ f32x4 gelu4(f32x4 v) { return (f32x4){gelu_tanh(v[0]), gelu_tanh(v[1]), gelu_tanh(v[2]), gelu_tanh(v[3])}; }
; __device__ __forceinline__ f32x4 sigm4(f32x4 v) { return (f32x4){sigmoid_f(v[0]), sigmoid_f(v[1]), sigmoid_f(v[2]), sigmoid_f(v[3])}; }
; __device__ __forceinline__ u32x4 pack8(f32x4 a, f32x4 b) { u32x4 w; w.x = cvt_pk_bf16(a[0], a[1]); w.y = cvt_pk_bf16(a[2], a[3]); w.z = cvt_pk_bf16(b[0], b[1]); w.w = cvt_pk_bf16(b[2], b[3]); return w; }
;     __device__ __forceinline__ void operator()(f32x4 (&acc)[2][2][4][2], const Unit& u, int wr, int wc, int fr, int fq) const {
;     ...
;             const int row0 = u.pm * BM + wr * 64 + fr, col0 = colt + wc * 64 + 8 * fq;
; #pragma unroll
;             for (int ai = 0; ai < 2; ++ai)
; #pragma unroll
;                 for (int m = 0; m < 4; ++m) {
;                     const int row = row0 + ai * HALF + m * 16;
;                     float rstd = row_rstd(ss, row, fq); if (mode == 1) rstd *= 0.125f;
;                     bf16_t* rowp = base + (size_t)row * ldc + col0;
; #pragma unroll
;                     for (int bj = 0; bj < 2; ++bj) {
;                         f32x4 v0 = acc[ai][bj][m][0] * rstd, v1 = acc[ai][bj][m][1] * rstd;
;                         if (mode == 3) { u32x2 w; w.x = gate_q4(sigm4(v0)); w.y = gate_q4(sigm4(v1)); *(u32x2*)((unsigned char*)Gt + (size_t)row * 4096 + col0 + bj * 32) = w; continue; }
;                         if (mode == 0) { v0 = gelu4(v0); v1 = gelu4(v1); }
;                         *(u32x4*)(rowp + bj * 32) = pack8(v0, v1);
	v_pk_mul_f32 v[108:109], v[108:109], v[140:141] op_sel_hi:[1,0]
	v_pk_mul_f32 v[110:111], v[110:111], v[140:141] op_sel_hi:[1,0]
	v_pk_mul_f32 v[104:105], v[104:105], v[140:141] op_sel_hi:[1,0]
	v_pk_mul_f32 v[106:107], v[106:107], v[140:141] op_sel_hi:[1,0]
	v_pk_mul_f32 v[100:101], v[100:101], v[140:141] op_sel_hi:[1,0]
	v_pk_mul_f32 v[102:103], v[102:103], v[140:141] op_sel_hi:[1,0]
	v_pk_mul_f32 v[96:97], v[96:97], v[152:153] op_sel_hi:[1,0]
	v_pk_mul_f32 v[98:99], v[98:99], v[152:153] op_sel_hi:[1,0]
	v_pk_mul_f32 v[92:93], v[92:93], v[152:153] op_sel_hi:[1,0]
	v_pk_mul_f32 v[94:95], v[94:95], v[152:153] op_sel_hi:[1,0]
	v_pk_mul_f32 v[88:89], v[88:89], v[152:153] op_sel_hi:[1,0]
	v_pk_mul_f32 v[90:91], v[90:91], v[152:153] op_sel_hi:[1,0]
	v_pk_mul_f32 v[84:85], v[84:85], v[152:153] op_sel_hi:[1,0]
	v_pk_mul_f32 v[86:87], v[86:87], v[152:153] op_sel_hi:[1,0]
	v_pk_mul_f32 v[80:81], v[80:81], v[188:189] op_sel_hi:[1,0]
	v_pk_mul_f32 v[82:83], v[82:83], v[188:189] op_sel_hi:[1,0]
	v_pk_mul_f32 v[76:77], v[76:77], v[188:189] op_sel_hi:[1,0]
	v_pk_mul_f32 v[78:79], v[78:79], v[188:189] op_sel_hi:[1,0]
	v_pk_mul_f32 v[72:73], v[72:73], v[188:189] op_sel_hi:[1,0]
	v_pk_mul_f32 v[74:75], v[74:75], v[188:189] op_sel_hi:[1,0]
	v_pk_mul_f32 v[68:69], v[68:69], v[188:189] op_sel_hi:[1,0]
	v_pk_mul_f32 v[70:71], v[70:71], v[188:189] op_sel_hi:[1,0]
	v_pk_mul_f32 v[64:65], v[64:65], v[196:197] op_sel_hi:[1,0]
	v_pk_mul_f32 v[66:67], v[66:67], v[196:197] op_sel_hi:[1,0]
	v_pk_mul_f32 v[60:61], v[60:61], v[196:197] op_sel_hi:[1,0]
	v_pk_mul_f32 v[62:63], v[62:63], v[196:197] op_sel_hi:[1,0]
	v_pk_mul_f32 v[56:57], v[56:57], v[196:197] op_sel_hi:[1,0]
	v_pk_mul_f32 v[58:59], v[58:59], v[196:197] op_sel_hi:[1,0]
	v_pk_mul_f32 v[52:53], v[52:53], v[196:197] op_sel_hi:[1,0]
	v_pk_mul_f32 v[54:55], v[54:55], v[196:197] op_sel_hi:[1,0]
	v_pk_mul_f32 v[48:49], v[48:49], v[204:205] op_sel_hi:[1,0]
	v_pk_mul_f32 v[50:51], v[50:51], v[204:205] op_sel_hi:[1,0]
	v_pk_mul_f32 v[44:45], v[44:45], v[204:205] op_sel_hi:[1,0]
	v_pk_mul_f32 v[46:47], v[46:47], v[204:205] op_sel_hi:[1,0]
	v_pk_mul_f32 v[40:41], v[40:41], v[204:205] op_sel_hi:[1,0]
	v_pk_mul_f32 v[42:43], v[42:43], v[204:205] op_sel_hi:[1,0]
	v_pk_mul_f32 v[36:37], v[36:37], v[204:205] op_sel_hi:[1,0]
	v_pk_mul_f32 v[38:39], v[38:39], v[204:205] op_sel_hi:[1,0]
	v_pk_mul_f32 v[32:33], v[32:33], v[222:223] op_sel_hi:[1,0]
	v_pk_mul_f32 v[34:35], v[34:35], v[222:223] op_sel_hi:[1,0]
	v_pk_mul_f32 v[28:29], v[28:29], v[222:223] op_sel_hi:[1,0]
	v_pk_mul_f32 v[30:31], v[30:31], v[222:223] op_sel_hi:[1,0]
	v_pk_mul_f32 v[24:25], v[24:25], v[222:223] op_sel_hi:[1,0]
	v_pk_mul_f32 v[26:27], v[26:27], v[222:223] op_sel_hi:[1,0]
	v_pk_mul_f32 v[20:21], v[20:21], v[222:223] op_sel_hi:[1,0]
	v_pk_mul_f32 v[22:23], v[22:23], v[222:223] op_sel_hi:[1,0]
	v_pk_mul_f32 v[16:17], v[16:17], v[246:247] op_sel_hi:[1,0]
	v_pk_mul_f32 v[18:19], v[18:19], v[246:247] op_sel_hi:[1,0]
	v_pk_mul_f32 v[12:13], v[12:13], v[246:247] op_sel_hi:[1,0]
	v_pk_mul_f32 v[14:15], v[14:15], v[246:247] op_sel_hi:[1,0]
	v_pk_mul_f32 v[8:9], v[8:9], v[246:247] op_sel_hi:[1,0]
	v_pk_mul_f32 v[10:11], v[10:11], v[246:247] op_sel_hi:[1,0]
	v_pk_mul_f32 v[4:5], v[4:5], v[246:247] op_sel_hi:[1,0]
	v_pk_mul_f32 v[6:7], v[6:7], v[246:247] op_sel_hi:[1,0]
	v_lshl_add_u32 v140, s82, 8, v211
	v_ashrrev_i32_e32 v141, 31, v140
	v_lshlrev_b64 v[2:3], 7, v[140:141]
	v_lshl_add_u64 v[2:3], v[178:179], 0, v[2:3]
	s_waitcnt lgkmcnt(0)
	v_and_b32_e32 v3, 64, v241
	v_xor_b32_e32 v0, 16, v241
	v_add_u32_e32 v146, 64, v3
	v_cmp_lt_i32_e32 vcc, v0, v146
	v_xor_b32_e32 v144, 32, v241
	v_add_u32_e32 v2, s20, v215
	v_cndmask_b32_e32 v0, v241, v0, vcc
	v_lshlrev_b32_e32 v0, 2, v0
	v_cmp_lt_i32_e32 vcc, v144, v146
	v_cndmask_b32_e64 v145, 0, 1, s[16:17]
	v_ashrrev_i32_e32 v3, 31, v2
	v_cmp_ne_u32_e64 s[38:39], 1, v145
	s_xor_b64 s[12:13], s[12:13], -1
	s_mov_b64 s[40:41], -1
	v_lshl_add_u64 v[142:143], v[2:3], 1, s[34:35]
	v_cndmask_b32_e32 v135, v241, v144, vcc
	v_lshlrev_b32_e32 v148, 2, v135
	v_mul_lo_u32 v134, s1, v140
	s_and_b64 vcc, exec, s[12:13]
	s_waitcnt lgkmcnt(0)
	v_mad_u64_u32 v[132:133], s[16:17], s0, v140, 0
	s_waitcnt lgkmcnt(0)
	v_mov_b32_e32 v135, 1.0
	v_mul_lo_u32 v136, s0, v141
	v_add3_u32 v133, v133, v136, v134
	v_lshl_add_u64 v[144:145], v[132:133], 1, v[142:143]
	v_mul_f32_e32 v132, 0x3e000000, v135
	v_cndmask_b32_e64 v146, v135, v132, s[18:19]
	v_pk_mul_f32 v[130:131], v[130:131], v[146:147] op_sel_hi:[1,0]
	v_pk_mul_f32 v[128:129], v[128:129], v[146:147] op_sel_hi:[1,0]
	v_pk_mul_f32 v[126:127], v[126:127], v[146:147] op_sel_hi:[1,0]
	v_pk_mul_f32 v[124:125], v[124:125], v[146:147] op_sel_hi:[1,0]
	s_cbranch_vccz .LBB0_247
	s_and_b64 vcc, exec, s[38:39]
	s_cbranch_vccnz .LBB0_245
	v_mul_f32_e32 v136, 0x3d372713, v124
	v_mul_f32_e32 v136, v124, v136
	v_fma_f32 v136, v124, v136, v124
	v_mul_f32_e32 v136, 0xc0135761, v136
	v_exp_f32_e32 v136, v136
	v_mul_f32_e32 v137, 0x3d372713, v126
	v_mul_f32_e32 v132, 0x3d372713, v128
	v_mul_f32_e32 v133, 0x3d372713, v129
	v_add_f32_e32 v136, 1.0, v136
	v_mul_f32_e32 v134, 0x3d372713, v130
	v_mul_f32_e32 v135, 0x3d372713, v131
	v_rcp_f32_e32 v150, v136
	v_mul_f32_e32 v136, 0x3d372713, v125
	v_mul_f32_e32 v137, v126, v137
	v_mul_f32_e32 v138, 0x3d372713, v127
	v_mul_f32_e32 v132, v128, v132
	v_mul_f32_e32 v133, v129, v133
	v_mul_f32_e32 v134, v130, v134
	v_mul_f32_e32 v135, v131, v135
	v_mul_f32_e32 v136, v125, v136
	v_fma_f32 v137, v126, v137, v126
	v_mul_f32_e32 v138, v127, v138
	v_fma_f32 v132, v128, v132, v128
	v_fma_f32 v133, v129, v133, v129
	v_fma_f32 v134, v130, v134, v130
	v_fma_f32 v135, v131, v135, v131
	v_fma_f32 v136, v125, v136, v125
	v_mul_f32_e32 v137, 0xc0135761, v137
	v_fma_f32 v138, v127, v138, v127
	v_mul_f32_e32 v132, 0xc0135761, v132
	v_mul_f32_e32 v133, 0xc0135761, v133
	v_mul_f32_e32 v134, 0xc0135761, v134
	v_mul_f32_e32 v135, 0xc0135761, v135
	v_mul_f32_e32 v136, 0xc0135761, v136
	v_exp_f32_e32 v137, v137
	v_mul_f32_e32 v138, 0xc0135761, v138
	v_exp_f32_e32 v132, v132
	v_exp_f32_e32 v133, v133
	v_exp_f32_e32 v134, v134
	v_exp_f32_e32 v135, v135
	v_exp_f32_e32 v136, v136
	v_exp_f32_e32 v138, v138
	v_add_f32_e32 v137, 1.0, v137
	v_add_f32_e32 v132, 1.0, v132
	v_add_f32_e32 v133, 1.0, v133
	v_add_f32_e32 v134, 1.0, v134
	v_add_f32_e32 v135, 1.0, v135
	v_add_f32_e32 v136, 1.0, v136
	v_rcp_f32_e32 v152, v137
	v_add_f32_e32 v137, 1.0, v138
	v_rcp_f32_e32 v132, v132
	v_rcp_f32_e32 v133, v133
	v_rcp_f32_e32 v134, v134
	v_rcp_f32_e32 v135, v135
	v_rcp_f32_e32 v153, v137
	v_rcp_f32_e32 v151, v136
	v_pk_mul_f32 v[136:137], v[128:129], v[132:133]
	v_pk_mul_f32 v[138:139], v[130:131], v[134:135]
	v_pk_mul_f32 v[134:135], v[126:127], v[152:153]
	v_pk_mul_f32 v[132:133], v[124:125], v[150:151]
	s_branch .LBB0_246

;     __device__ __forceinline__ void operator()(f32x4 (&acc)[2][2][4][2], const Unit& u, int wr, int wc, int fr, int fq) const {
;     ...
;                     const int row = row0 + ai * HALF + m * 16;
;                     float rstd = row_rstd(ss, row, fq); if (mode == 1) rstd *= 0.125f;
;                     bf16_t* rowp = base + (size_t)row * ldc + col0;
; #pragma unroll
;                     for (int bj = 0; bj < 2; ++bj) {
;                         f32x4 v0 = acc[ai][bj][m][0] * rstd, v1 = acc[ai][bj][m][1] * rstd;
.LBB0_256:
	v_or_b32_e32 v128, 16, v140
	v_ashrrev_i32_e32 v129, 31, v128
	v_lshlrev_b64 v[116:117], 7, v[128:129]
	v_lshl_add_u64 v[120:121], v[178:179], 0, v[116:117]
	s_nop 0
	s_and_b64 vcc, exec, s[40:41]
	v_mul_lo_u32 v120, s1, v128
	s_nop 0
	s_waitcnt lgkmcnt(0)
	v_mad_u64_u32 v[116:117], s[12:13], s0, v128, 0
	s_mov_b64 s[12:13], -1
	s_waitcnt lgkmcnt(0)
	v_mov_b32_e32 v118, 1.0
	v_mul_lo_u32 v119, s0, v129
	v_add3_u32 v117, v117, v119, v120
	v_lshl_add_u64 v[124:125], v[116:117], 1, v[142:143]
	v_mul_f32_e32 v116, 0x3e000000, v118
	v_cndmask_b32_e64 v126, v118, v116, s[18:19]
	v_pk_mul_f32 v[114:115], v[114:115], v[126:127] op_sel_hi:[1,0]
	v_pk_mul_f32 v[112:113], v[112:113], v[126:127] op_sel_hi:[1,0]
	v_pk_mul_f32 v[110:111], v[110:111], v[126:127] op_sel_hi:[1,0]
	v_pk_mul_f32 v[108:109], v[108:109], v[126:127] op_sel_hi:[1,0]
	s_cbranch_vccnz .LBB0_261
	s_and_b64 vcc, exec, s[38:39]
	s_cbranch_vccnz .LBB0_259
	v_mul_f32_e32 v120, 0x3d372713, v108
	v_mul_f32_e32 v120, v108, v120
	v_fma_f32 v120, v108, v120, v108
	v_mul_f32_e32 v120, 0xc0135761, v120
	v_exp_f32_e32 v120, v120
	v_mul_f32_e32 v121, 0x3d372713, v110
	v_mul_f32_e32 v116, 0x3d372713, v112
	v_mul_f32_e32 v117, 0x3d372713, v113
	v_add_f32_e32 v120, 1.0, v120
	v_mul_f32_e32 v118, 0x3d372713, v114
	v_mul_f32_e32 v119, 0x3d372713, v115
	v_rcp_f32_e32 v130, v120
	v_mul_f32_e32 v120, 0x3d372713, v109
	v_mul_f32_e32 v121, v110, v121
	v_mul_f32_e32 v122, 0x3d372713, v111
	v_mul_f32_e32 v116, v112, v116
	v_mul_f32_e32 v117, v113, v117
	v_mul_f32_e32 v118, v114, v118
	v_mul_f32_e32 v119, v115, v119
	v_mul_f32_e32 v120, v109, v120
	v_fma_f32 v121, v110, v121, v110
	v_mul_f32_e32 v122, v111, v122
	v_fma_f32 v116, v112, v116, v112
	v_fma_f32 v117, v113, v117, v113
	v_fma_f32 v118, v114, v118, v114
	v_fma_f32 v119, v115, v119, v115
	v_fma_f32 v120, v109, v120, v109
	v_mul_f32_e32 v121, 0xc0135761, v121
	v_fma_f32 v122, v111, v122, v111
	v_mul_f32_e32 v116, 0xc0135761, v116
	v_mul_f32_e32 v117, 0xc0135761, v117
	v_mul_f32_e32 v118, 0xc0135761, v118
	v_mul_f32_e32 v119, 0xc0135761, v119
	v_mul_f32_e32 v120, 0xc0135761, v120
	v_exp_f32_e32 v121, v121
	v_mul_f32_e32 v122, 0xc0135761, v122
	v_exp_f32_e32 v116, v116
	v_exp_f32_e32 v117, v117
	v_exp_f32_e32 v118, v118
	v_exp_f32_e32 v119, v119
	v_exp_f32_e32 v120, v120
	v_exp_f32_e32 v122, v122
	v_add_f32_e32 v121, 1.0, v121
	v_add_f32_e32 v116, 1.0, v116
	v_add_f32_e32 v117, 1.0, v117
	v_add_f32_e32 v118, 1.0, v118
	v_add_f32_e32 v119, 1.0, v119
	v_add_f32_e32 v120, 1.0, v120
	v_rcp_f32_e32 v132, v121
	v_add_f32_e32 v121, 1.0, v122
	v_rcp_f32_e32 v116, v116
	v_rcp_f32_e32 v117, v117
	v_rcp_f32_e32 v118, v118
	v_rcp_f32_e32 v119, v119
	v_rcp_f32_e32 v133, v121
	v_rcp_f32_e32 v131, v120
	v_pk_mul_f32 v[120:121], v[112:113], v[116:117]
	v_pk_mul_f32 v[122:123], v[114:115], v[118:119]
	v_pk_mul_f32 v[118:119], v[110:111], v[132:133]
	v_pk_mul_f32 v[116:117], v[108:109], v[130:131]
	s_branch .LBB0_260

;     __device__ __forceinline__ void operator()(f32x4 (&acc)[2][2][4][2], const Unit& u, int wr, int wc, int fr, int fq) const {
;     ...
;                     const int row = row0 + ai * HALF + m * 16;
;                     float rstd = row_rstd(ss, row, fq); if (mode == 1) rstd *= 0.125f;
;                     bf16_t* rowp = base + (size_t)row * ldc + col0;
; #pragma unroll
;                     for (int bj = 0; bj < 2; ++bj) {
;                         f32x4 v0 = acc[ai][bj][m][0] * rstd, v1 = acc[ai][bj][m][1] * rstd;
.LBB0_270:
	v_or_b32_e32 v112, 32, v140
	v_ashrrev_i32_e32 v113, 31, v112
	v_lshlrev_b64 v[100:101], 7, v[112:113]
	v_lshl_add_u64 v[104:105], v[178:179], 0, v[100:101]
	s_nop 0
	s_and_b64 vcc, exec, s[40:41]
	v_mul_lo_u32 v104, s1, v112
	s_nop 0
	s_waitcnt lgkmcnt(0)
	v_mad_u64_u32 v[100:101], s[12:13], s0, v112, 0
	s_mov_b64 s[12:13], -1
	s_waitcnt lgkmcnt(0)
	v_mov_b32_e32 v102, 1.0
	v_mul_lo_u32 v103, s0, v113
	v_add3_u32 v101, v101, v103, v104
	v_lshl_add_u64 v[108:109], v[100:101], 1, v[142:143]
	v_mul_f32_e32 v100, 0x3e000000, v102
	v_cndmask_b32_e64 v110, v102, v100, s[18:19]
	v_pk_mul_f32 v[98:99], v[98:99], v[110:111] op_sel_hi:[1,0]
	v_pk_mul_f32 v[96:97], v[96:97], v[110:111] op_sel_hi:[1,0]
	v_pk_mul_f32 v[94:95], v[94:95], v[110:111] op_sel_hi:[1,0]
	v_pk_mul_f32 v[92:93], v[92:93], v[110:111] op_sel_hi:[1,0]
	s_cbranch_vccnz .LBB0_275
	s_and_b64 vcc, exec, s[38:39]
	s_cbranch_vccnz .LBB0_273
	v_mul_f32_e32 v104, 0x3d372713, v92
	v_mul_f32_e32 v104, v92, v104
	v_fma_f32 v104, v92, v104, v92
	v_mul_f32_e32 v104, 0xc0135761, v104
	v_exp_f32_e32 v104, v104
	v_mul_f32_e32 v105, 0x3d372713, v94
	v_mul_f32_e32 v100, 0x3d372713, v96
	v_mul_f32_e32 v101, 0x3d372713, v97
	v_add_f32_e32 v104, 1.0, v104
	v_mul_f32_e32 v102, 0x3d372713, v98
	v_mul_f32_e32 v103, 0x3d372713, v99
	v_rcp_f32_e32 v114, v104
	v_mul_f32_e32 v104, 0x3d372713, v93
	v_mul_f32_e32 v105, v94, v105
	v_mul_f32_e32 v106, 0x3d372713, v95
	v_mul_f32_e32 v100, v96, v100
	v_mul_f32_e32 v101, v97, v101
	v_mul_f32_e32 v102, v98, v102
	v_mul_f32_e32 v103, v99, v103
	v_mul_f32_e32 v104, v93, v104
	v_fma_f32 v105, v94, v105, v94
	v_mul_f32_e32 v106, v95, v106
	v_fma_f32 v100, v96, v100, v96
	v_fma_f32 v101, v97, v101, v97
	v_fma_f32 v102, v98, v102, v98
	v_fma_f32 v103, v99, v103, v99
	v_fma_f32 v104, v93, v104, v93
	v_mul_f32_e32 v105, 0xc0135761, v105
	v_fma_f32 v106, v95, v106, v95
	v_mul_f32_e32 v100, 0xc0135761, v100
	v_mul_f32_e32 v101, 0xc0135761, v101
	v_mul_f32_e32 v102, 0xc0135761, v102
	v_mul_f32_e32 v103, 0xc0135761, v103
	v_mul_f32_e32 v104, 0xc0135761, v104
	v_exp_f32_e32 v105, v105
	v_mul_f32_e32 v106, 0xc0135761, v106
	v_exp_f32_e32 v100, v100
	v_exp_f32_e32 v101, v101
	v_exp_f32_e32 v102, v102
	v_exp_f32_e32 v103, v103
	v_exp_f32_e32 v104, v104
	v_exp_f32_e32 v106, v106
	v_add_f32_e32 v105, 1.0, v105
	v_add_f32_e32 v100, 1.0, v100
	v_add_f32_e32 v101, 1.0, v101
	v_add_f32_e32 v102, 1.0, v102
	v_add_f32_e32 v103, 1.0, v103
	v_add_f32_e32 v104, 1.0, v104
	v_rcp_f32_e32 v116, v105
	v_add_f32_e32 v105, 1.0, v106
	v_rcp_f32_e32 v100, v100
	v_rcp_f32_e32 v101, v101
	v_rcp_f32_e32 v102, v102
	v_rcp_f32_e32 v103, v103
	v_rcp_f32_e32 v117, v105
	v_rcp_f32_e32 v115, v104
	v_pk_mul_f32 v[104:105], v[96:97], v[100:101]
	v_pk_mul_f32 v[106:107], v[98:99], v[102:103]
	v_pk_mul_f32 v[102:103], v[94:95], v[116:117]
	v_pk_mul_f32 v[100:101], v[92:93], v[114:115]
	s_branch .LBB0_274

;     __device__ __forceinline__ void operator()(f32x4 (&acc)[2][2][4][2], const Unit& u, int wr, int wc, int fr, int fq) const {
;     ...
;                     const int row = row0 + ai * HALF + m * 16;
;                     float rstd = row_rstd(ss, row, fq); if (mode == 1) rstd *= 0.125f;
;                     bf16_t* rowp = base + (size_t)row * ldc + col0;
; #pragma unroll
;                     for (int bj = 0; bj < 2; ++bj) {
;                         f32x4 v0 = acc[ai][bj][m][0] * rstd, v1 = acc[ai][bj][m][1] * rstd;
.LBB0_284:
	v_or_b32_e32 v96, 48, v140
	v_ashrrev_i32_e32 v97, 31, v96
	v_lshlrev_b64 v[84:85], 7, v[96:97]
	v_lshl_add_u64 v[88:89], v[178:179], 0, v[84:85]
	s_nop 0
	s_and_b64 vcc, exec, s[40:41]
	v_mul_lo_u32 v88, s1, v96
	s_nop 0
	s_waitcnt lgkmcnt(0)
	v_mad_u64_u32 v[84:85], s[12:13], s0, v96, 0
	s_mov_b64 s[12:13], -1
	s_waitcnt lgkmcnt(0)
	v_mov_b32_e32 v86, 1.0
	v_mul_lo_u32 v87, s0, v97
	v_add3_u32 v85, v85, v87, v88
	v_lshl_add_u64 v[92:93], v[84:85], 1, v[142:143]
	v_mul_f32_e32 v84, 0x3e000000, v86
	v_cndmask_b32_e64 v94, v86, v84, s[18:19]
	v_pk_mul_f32 v[82:83], v[82:83], v[94:95] op_sel_hi:[1,0]
	v_pk_mul_f32 v[80:81], v[80:81], v[94:95] op_sel_hi:[1,0]
	v_pk_mul_f32 v[78:79], v[78:79], v[94:95] op_sel_hi:[1,0]
	v_pk_mul_f32 v[76:77], v[76:77], v[94:95] op_sel_hi:[1,0]
	s_cbranch_vccnz .LBB0_289
	s_and_b64 vcc, exec, s[38:39]
	s_cbranch_vccnz .LBB0_287
	v_mul_f32_e32 v88, 0x3d372713, v76
	v_mul_f32_e32 v88, v76, v88
	v_fma_f32 v88, v76, v88, v76
	v_mul_f32_e32 v88, 0xc0135761, v88
	v_exp_f32_e32 v88, v88
	v_mul_f32_e32 v89, 0x3d372713, v78
	v_mul_f32_e32 v84, 0x3d372713, v80
	v_mul_f32_e32 v85, 0x3d372713, v81
	v_add_f32_e32 v88, 1.0, v88
	v_mul_f32_e32 v86, 0x3d372713, v82
	v_mul_f32_e32 v87, 0x3d372713, v83
	v_rcp_f32_e32 v98, v88
	v_mul_f32_e32 v88, 0x3d372713, v77
	v_mul_f32_e32 v89, v78, v89
	v_mul_f32_e32 v90, 0x3d372713, v79
	v_mul_f32_e32 v84, v80, v84
	v_mul_f32_e32 v85, v81, v85
	v_mul_f32_e32 v86, v82, v86
	v_mul_f32_e32 v87, v83, v87
	v_mul_f32_e32 v88, v77, v88
	v_fma_f32 v89, v78, v89, v78
	v_mul_f32_e32 v90, v79, v90
	v_fma_f32 v84, v80, v84, v80
	v_fma_f32 v85, v81, v85, v81
	v_fma_f32 v86, v82, v86, v82
	v_fma_f32 v87, v83, v87, v83
	v_fma_f32 v88, v77, v88, v77
	v_mul_f32_e32 v89, 0xc0135761, v89
	v_fma_f32 v90, v79, v90, v79
	v_mul_f32_e32 v84, 0xc0135761, v84
	v_mul_f32_e32 v85, 0xc0135761, v85
	v_mul_f32_e32 v86, 0xc0135761, v86
	v_mul_f32_e32 v87, 0xc0135761, v87
	v_mul_f32_e32 v88, 0xc0135761, v88
	v_exp_f32_e32 v89, v89
	v_mul_f32_e32 v90, 0xc0135761, v90
	v_exp_f32_e32 v84, v84
	v_exp_f32_e32 v85, v85
	v_exp_f32_e32 v86, v86
	v_exp_f32_e32 v87, v87
	v_exp_f32_e32 v88, v88
	v_exp_f32_e32 v90, v90
	v_add_f32_e32 v89, 1.0, v89
	v_add_f32_e32 v84, 1.0, v84
	v_add_f32_e32 v85, 1.0, v85
	v_add_f32_e32 v86, 1.0, v86
	v_add_f32_e32 v87, 1.0, v87
	v_add_f32_e32 v88, 1.0, v88
	v_rcp_f32_e32 v100, v89
	v_add_f32_e32 v89, 1.0, v90
	v_rcp_f32_e32 v84, v84
	v_rcp_f32_e32 v85, v85
	v_rcp_f32_e32 v86, v86
	v_rcp_f32_e32 v87, v87
	v_rcp_f32_e32 v101, v89
	v_rcp_f32_e32 v99, v88
	v_pk_mul_f32 v[88:89], v[80:81], v[84:85]
	v_pk_mul_f32 v[90:91], v[82:83], v[86:87]
	v_pk_mul_f32 v[86:87], v[78:79], v[100:101]
	v_pk_mul_f32 v[84:85], v[76:77], v[98:99]
	s_branch .LBB0_288

;     __device__ __forceinline__ void operator()(f32x4 (&acc)[2][2][4][2], const Unit& u, int wr, int wc, int fr, int fq) const {
;     ...
;                     const int row = row0 + ai * HALF + m * 16;
;                     float rstd = row_rstd(ss, row, fq); if (mode == 1) rstd *= 0.125f;
;                     bf16_t* rowp = base + (size_t)row * ldc + col0;
; #pragma unroll
;                     for (int bj = 0; bj < 2; ++bj) {
;                         f32x4 v0 = acc[ai][bj][m][0] * rstd, v1 = acc[ai][bj][m][1] * rstd;
.LBB0_298:
	v_add_u32_e32 v80, 0x80, v140
	v_ashrrev_i32_e32 v81, 31, v80
	v_lshlrev_b64 v[68:69], 7, v[80:81]
	v_lshl_add_u64 v[72:73], v[178:179], 0, v[68:69]
	s_nop 0
	s_and_b64 vcc, exec, s[40:41]
	v_mul_lo_u32 v72, s1, v80
	s_nop 0
	s_waitcnt lgkmcnt(0)
	v_mad_u64_u32 v[68:69], s[12:13], s0, v80, 0
	s_mov_b64 s[12:13], -1
	s_waitcnt lgkmcnt(0)
	v_mov_b32_e32 v70, 1.0
	v_mul_lo_u32 v71, s0, v81
	v_add3_u32 v69, v69, v71, v72
	v_lshl_add_u64 v[76:77], v[68:69], 1, v[142:143]
	v_mul_f32_e32 v68, 0x3e000000, v70
	v_cndmask_b32_e64 v78, v70, v68, s[18:19]
	v_pk_mul_f32 v[66:67], v[66:67], v[78:79] op_sel_hi:[1,0]
	v_pk_mul_f32 v[64:65], v[64:65], v[78:79] op_sel_hi:[1,0]
	v_pk_mul_f32 v[62:63], v[62:63], v[78:79] op_sel_hi:[1,0]
	v_pk_mul_f32 v[60:61], v[60:61], v[78:79] op_sel_hi:[1,0]
	s_cbranch_vccnz .LBB0_303
	s_and_b64 vcc, exec, s[38:39]
	s_cbranch_vccnz .LBB0_301
	v_mul_f32_e32 v72, 0x3d372713, v60
	v_mul_f32_e32 v72, v60, v72
	v_fma_f32 v72, v60, v72, v60
	v_mul_f32_e32 v72, 0xc0135761, v72
	v_exp_f32_e32 v72, v72
	v_mul_f32_e32 v73, 0x3d372713, v62
	v_mul_f32_e32 v68, 0x3d372713, v64
	v_mul_f32_e32 v69, 0x3d372713, v65
	v_add_f32_e32 v72, 1.0, v72
	v_mul_f32_e32 v70, 0x3d372713, v66
	v_mul_f32_e32 v71, 0x3d372713, v67
	v_rcp_f32_e32 v82, v72
	v_mul_f32_e32 v72, 0x3d372713, v61
	v_mul_f32_e32 v73, v62, v73
	v_mul_f32_e32 v74, 0x3d372713, v63
	v_mul_f32_e32 v68, v64, v68
	v_mul_f32_e32 v69, v65, v69
	v_mul_f32_e32 v70, v66, v70
	v_mul_f32_e32 v71, v67, v71
	v_mul_f32_e32 v72, v61, v72
	v_fma_f32 v73, v62, v73, v62
	v_mul_f32_e32 v74, v63, v74
	v_fma_f32 v68, v64, v68, v64
	v_fma_f32 v69, v65, v69, v65
	v_fma_f32 v70, v66, v70, v66
	v_fma_f32 v71, v67, v71, v67
	v_fma_f32 v72, v61, v72, v61
	v_mul_f32_e32 v73, 0xc0135761, v73
	v_fma_f32 v74, v63, v74, v63
	v_mul_f32_e32 v68, 0xc0135761, v68
	v_mul_f32_e32 v69, 0xc0135761, v69
	v_mul_f32_e32 v70, 0xc0135761, v70
	v_mul_f32_e32 v71, 0xc0135761, v71
	v_mul_f32_e32 v72, 0xc0135761, v72
	v_exp_f32_e32 v73, v73
	v_mul_f32_e32 v74, 0xc0135761, v74
	v_exp_f32_e32 v68, v68
	v_exp_f32_e32 v69, v69
	v_exp_f32_e32 v70, v70
	v_exp_f32_e32 v71, v71
	v_exp_f32_e32 v72, v72
	v_exp_f32_e32 v74, v74
	v_add_f32_e32 v73, 1.0, v73
	v_add_f32_e32 v68, 1.0, v68
	v_add_f32_e32 v69, 1.0, v69
	v_add_f32_e32 v70, 1.0, v70
	v_add_f32_e32 v71, 1.0, v71
	v_add_f32_e32 v72, 1.0, v72
	v_rcp_f32_e32 v84, v73
	v_add_f32_e32 v73, 1.0, v74
	v_rcp_f32_e32 v68, v68
	v_rcp_f32_e32 v69, v69
	v_rcp_f32_e32 v70, v70
	v_rcp_f32_e32 v71, v71
	v_rcp_f32_e32 v85, v73
	v_rcp_f32_e32 v83, v72
	v_pk_mul_f32 v[72:73], v[64:65], v[68:69]
	v_pk_mul_f32 v[74:75], v[66:67], v[70:71]
	v_pk_mul_f32 v[70:71], v[62:63], v[84:85]
	v_pk_mul_f32 v[68:69], v[60:61], v[82:83]
	s_branch .LBB0_302

;     __device__ __forceinline__ void operator()(f32x4 (&acc)[2][2][4][2], const Unit& u, int wr, int wc, int fr, int fq) const {
;     ...
;                     const int row = row0 + ai * HALF + m * 16;
;                     float rstd = row_rstd(ss, row, fq); if (mode == 1) rstd *= 0.125f;
;                     bf16_t* rowp = base + (size_t)row * ldc + col0;
; #pragma unroll
;                     for (int bj = 0; bj < 2; ++bj) {
;                         f32x4 v0 = acc[ai][bj][m][0] * rstd, v1 = acc[ai][bj][m][1] * rstd;
.LBB0_312:
	v_add_u32_e32 v64, 0x90, v140
	v_ashrrev_i32_e32 v65, 31, v64
	v_lshlrev_b64 v[52:53], 7, v[64:65]
	v_lshl_add_u64 v[56:57], v[178:179], 0, v[52:53]
	s_nop 0
	s_and_b64 vcc, exec, s[40:41]
	v_mul_lo_u32 v56, s1, v64
	s_nop 0
	s_waitcnt lgkmcnt(0)
	v_mad_u64_u32 v[52:53], s[12:13], s0, v64, 0
	s_mov_b64 s[12:13], -1
	s_waitcnt lgkmcnt(0)
	v_mov_b32_e32 v54, 1.0
	v_mul_lo_u32 v55, s0, v65
	v_add3_u32 v53, v53, v55, v56
	v_lshl_add_u64 v[60:61], v[52:53], 1, v[142:143]
	v_mul_f32_e32 v52, 0x3e000000, v54
	v_cndmask_b32_e64 v62, v54, v52, s[18:19]
	v_pk_mul_f32 v[50:51], v[50:51], v[62:63] op_sel_hi:[1,0]
	v_pk_mul_f32 v[48:49], v[48:49], v[62:63] op_sel_hi:[1,0]
	v_pk_mul_f32 v[46:47], v[46:47], v[62:63] op_sel_hi:[1,0]
	v_pk_mul_f32 v[44:45], v[44:45], v[62:63] op_sel_hi:[1,0]
	s_cbranch_vccnz .LBB0_317
	s_and_b64 vcc, exec, s[38:39]
	s_cbranch_vccnz .LBB0_315
	v_mul_f32_e32 v56, 0x3d372713, v44
	v_mul_f32_e32 v56, v44, v56
	v_fma_f32 v56, v44, v56, v44
	v_mul_f32_e32 v56, 0xc0135761, v56
	v_exp_f32_e32 v56, v56
	v_mul_f32_e32 v57, 0x3d372713, v46
	v_mul_f32_e32 v52, 0x3d372713, v48
	v_mul_f32_e32 v53, 0x3d372713, v49
	v_add_f32_e32 v56, 1.0, v56
	v_mul_f32_e32 v54, 0x3d372713, v50
	v_mul_f32_e32 v55, 0x3d372713, v51
	v_rcp_f32_e32 v66, v56
	v_mul_f32_e32 v56, 0x3d372713, v45
	v_mul_f32_e32 v57, v46, v57
	v_mul_f32_e32 v58, 0x3d372713, v47
	v_mul_f32_e32 v52, v48, v52
	v_mul_f32_e32 v53, v49, v53
	v_mul_f32_e32 v54, v50, v54
	v_mul_f32_e32 v55, v51, v55
	v_mul_f32_e32 v56, v45, v56
	v_fma_f32 v57, v46, v57, v46
	v_mul_f32_e32 v58, v47, v58
	v_fma_f32 v52, v48, v52, v48
	v_fma_f32 v53, v49, v53, v49
	v_fma_f32 v54, v50, v54, v50
	v_fma_f32 v55, v51, v55, v51
	v_fma_f32 v56, v45, v56, v45
	v_mul_f32_e32 v57, 0xc0135761, v57
	v_fma_f32 v58, v47, v58, v47
	v_mul_f32_e32 v52, 0xc0135761, v52
	v_mul_f32_e32 v53, 0xc0135761, v53
	v_mul_f32_e32 v54, 0xc0135761, v54
	v_mul_f32_e32 v55, 0xc0135761, v55
	v_mul_f32_e32 v56, 0xc0135761, v56
	v_exp_f32_e32 v57, v57
	v_mul_f32_e32 v58, 0xc0135761, v58
	v_exp_f32_e32 v52, v52
	v_exp_f32_e32 v53, v53
	v_exp_f32_e32 v54, v54
	v_exp_f32_e32 v55, v55
	v_exp_f32_e32 v56, v56
	v_exp_f32_e32 v58, v58
	v_add_f32_e32 v57, 1.0, v57
	v_add_f32_e32 v52, 1.0, v52
	v_add_f32_e32 v53, 1.0, v53
	v_add_f32_e32 v54, 1.0, v54
	v_add_f32_e32 v55, 1.0, v55
	v_add_f32_e32 v56, 1.0, v56
	v_rcp_f32_e32 v68, v57
	v_add_f32_e32 v57, 1.0, v58
	v_rcp_f32_e32 v52, v52
	v_rcp_f32_e32 v53, v53
	v_rcp_f32_e32 v54, v54
	v_rcp_f32_e32 v55, v55
	v_rcp_f32_e32 v69, v57
	v_rcp_f32_e32 v67, v56
	v_pk_mul_f32 v[56:57], v[48:49], v[52:53]
	v_pk_mul_f32 v[58:59], v[50:51], v[54:55]
	v_pk_mul_f32 v[54:55], v[46:47], v[68:69]
	v_pk_mul_f32 v[52:53], v[44:45], v[66:67]
	s_branch .LBB0_316

;     __device__ __forceinline__ void operator()(f32x4 (&acc)[2][2][4][2], const Unit& u, int wr, int wc, int fr, int fq) const {
;     ...
;                     const int row = row0 + ai * HALF + m * 16;
;                     float rstd = row_rstd(ss, row, fq); if (mode == 1) rstd *= 0.125f;
;                     bf16_t* rowp = base + (size_t)row * ldc + col0;
; #pragma unroll
;                     for (int bj = 0; bj < 2; ++bj) {
;                         f32x4 v0 = acc[ai][bj][m][0] * rstd, v1 = acc[ai][bj][m][1] * rstd;
.LBB0_326:
	v_add_u32_e32 v48, 0xa0, v140
	v_ashrrev_i32_e32 v49, 31, v48
	v_lshlrev_b64 v[36:37], 7, v[48:49]
	v_lshl_add_u64 v[40:41], v[178:179], 0, v[36:37]
	s_nop 0
	s_and_b64 vcc, exec, s[40:41]
	v_mul_lo_u32 v40, s1, v48
	s_nop 0
	s_waitcnt lgkmcnt(0)
	v_mad_u64_u32 v[36:37], s[12:13], s0, v48, 0
	s_mov_b64 s[12:13], -1
	s_waitcnt lgkmcnt(0)
	v_mov_b32_e32 v38, 1.0
	v_mul_lo_u32 v39, s0, v49
	v_add3_u32 v37, v37, v39, v40
	v_lshl_add_u64 v[44:45], v[36:37], 1, v[142:143]
	v_mul_f32_e32 v36, 0x3e000000, v38
	v_cndmask_b32_e64 v46, v38, v36, s[18:19]
	v_pk_mul_f32 v[34:35], v[34:35], v[46:47] op_sel_hi:[1,0]
	v_pk_mul_f32 v[32:33], v[32:33], v[46:47] op_sel_hi:[1,0]
	v_pk_mul_f32 v[30:31], v[30:31], v[46:47] op_sel_hi:[1,0]
	v_pk_mul_f32 v[28:29], v[28:29], v[46:47] op_sel_hi:[1,0]
	s_cbranch_vccnz .LBB0_331
	s_and_b64 vcc, exec, s[38:39]
	s_cbranch_vccnz .LBB0_329
	v_mul_f32_e32 v40, 0x3d372713, v28
	v_mul_f32_e32 v40, v28, v40
	v_fma_f32 v40, v28, v40, v28
	v_mul_f32_e32 v40, 0xc0135761, v40
	v_exp_f32_e32 v40, v40
	v_mul_f32_e32 v41, 0x3d372713, v30
	v_mul_f32_e32 v36, 0x3d372713, v32
	v_mul_f32_e32 v37, 0x3d372713, v33
	v_add_f32_e32 v40, 1.0, v40
	v_mul_f32_e32 v38, 0x3d372713, v34
	v_mul_f32_e32 v39, 0x3d372713, v35
	v_rcp_f32_e32 v50, v40
	v_mul_f32_e32 v40, 0x3d372713, v29
	v_mul_f32_e32 v41, v30, v41
	v_mul_f32_e32 v42, 0x3d372713, v31
	v_mul_f32_e32 v36, v32, v36
	v_mul_f32_e32 v37, v33, v37
	v_mul_f32_e32 v38, v34, v38
	v_mul_f32_e32 v39, v35, v39
	v_mul_f32_e32 v40, v29, v40
	v_fma_f32 v41, v30, v41, v30
	v_mul_f32_e32 v42, v31, v42
	v_fma_f32 v36, v32, v36, v32
	v_fma_f32 v37, v33, v37, v33
	v_fma_f32 v38, v34, v38, v34
	v_fma_f32 v39, v35, v39, v35
	v_fma_f32 v40, v29, v40, v29
	v_mul_f32_e32 v41, 0xc0135761, v41
	v_fma_f32 v42, v31, v42, v31
	v_mul_f32_e32 v36, 0xc0135761, v36
	v_mul_f32_e32 v37, 0xc0135761, v37
	v_mul_f32_e32 v38, 0xc0135761, v38
	v_mul_f32_e32 v39, 0xc0135761, v39
	v_mul_f32_e32 v40, 0xc0135761, v40
	v_exp_f32_e32 v41, v41
	v_mul_f32_e32 v42, 0xc0135761, v42
	v_exp_f32_e32 v36, v36
	v_exp_f32_e32 v37, v37
	v_exp_f32_e32 v38, v38
	v_exp_f32_e32 v39, v39
	v_exp_f32_e32 v40, v40
	v_exp_f32_e32 v42, v42
	v_add_f32_e32 v41, 1.0, v41
	v_add_f32_e32 v36, 1.0, v36
	v_add_f32_e32 v37, 1.0, v37
	v_add_f32_e32 v38, 1.0, v38
	v_add_f32_e32 v39, 1.0, v39
	v_add_f32_e32 v40, 1.0, v40
	v_rcp_f32_e32 v52, v41
	v_add_f32_e32 v41, 1.0, v42
	v_rcp_f32_e32 v36, v36
	v_rcp_f32_e32 v37, v37
	v_rcp_f32_e32 v38, v38
	v_rcp_f32_e32 v39, v39
	v_rcp_f32_e32 v53, v41
	v_rcp_f32_e32 v51, v40
	v_pk_mul_f32 v[40:41], v[32:33], v[36:37]
	v_pk_mul_f32 v[42:43], v[34:35], v[38:39]
	v_pk_mul_f32 v[38:39], v[30:31], v[52:53]
	v_pk_mul_f32 v[36:37], v[28:29], v[50:51]
	s_branch .LBB0_330

;     __device__ __forceinline__ void operator()(f32x4 (&acc)[2][2][4][2], const Unit& u, int wr, int wc, int fr, int fq) const {
;     ...
;                     const int row = row0 + ai * HALF + m * 16;
;                     float rstd = row_rstd(ss, row, fq); if (mode == 1) rstd *= 0.125f;
;                     bf16_t* rowp = base + (size_t)row * ldc + col0;
; #pragma unroll
;                     for (int bj = 0; bj < 2; ++bj) {
;                         f32x4 v0 = acc[ai][bj][m][0] * rstd, v1 = acc[ai][bj][m][1] * rstd;
.LBB0_340:
	v_add_u32_e32 v32, 0xb0, v140
	v_ashrrev_i32_e32 v33, 31, v32
	v_lshlrev_b64 v[20:21], 7, v[32:33]
	v_lshl_add_u64 v[24:25], v[178:179], 0, v[20:21]
	s_nop 0
	s_and_b64 vcc, exec, s[40:41]
	s_nop 0
	v_mul_lo_u32 v22, s1, v32
	s_waitcnt lgkmcnt(0)
	s_waitcnt lgkmcnt(0)
	v_mov_b32_e32 v0, 1.0
	s_nop 0
	v_mul_f32_e32 v20, 0x3e000000, v0
	v_cndmask_b32_e64 v30, v0, v20, s[18:19]
	v_mul_lo_u32 v0, s0, v33
	v_mad_u64_u32 v[20:21], s[0:1], s0, v32, 0
	v_add3_u32 v21, v21, v0, v22
	v_lshl_add_u64 v[28:29], v[20:21], 1, v[142:143]
	v_pk_mul_f32 v[18:19], v[18:19], v[30:31] op_sel_hi:[1,0]
	v_pk_mul_f32 v[16:17], v[16:17], v[30:31] op_sel_hi:[1,0]
	v_pk_mul_f32 v[14:15], v[14:15], v[30:31] op_sel_hi:[1,0]
	v_pk_mul_f32 v[12:13], v[12:13], v[30:31] op_sel_hi:[1,0]
	s_mov_b64 s[0:1], -1
	s_cbranch_vccnz .LBB0_345
	s_and_b64 vcc, exec, s[38:39]
	s_cbranch_vccnz .LBB0_343
	v_mul_f32_e32 v20, 0x3d372713, v17
	v_mul_f32_e32 v20, v17, v20
	v_mul_f32_e32 v0, 0x3d372713, v16
	v_fma_f32 v20, v17, v20, v17
	v_mul_f32_e32 v0, v16, v0
	v_mul_f32_e32 v20, 0xc0135761, v20
	v_fma_f32 v0, v16, v0, v16
	v_exp_f32_e32 v21, v20
	v_mul_f32_e32 v20, 0x3d372713, v18
	v_mul_f32_e32 v0, 0xc0135761, v0
	v_mul_f32_e32 v20, v18, v20
	v_exp_f32_e32 v0, v0
	v_fma_f32 v20, v18, v20, v18
	v_mul_f32_e32 v20, 0xc0135761, v20
	v_exp_f32_e32 v22, v20
	v_add_f32_e32 v0, 1.0, v0
	v_rcp_f32_e32 v20, v0
	v_add_f32_e32 v0, 1.0, v21
	v_rcp_f32_e32 v21, v0
	v_add_f32_e32 v0, 1.0, v22
	v_mul_f32_e32 v22, 0x3d372713, v19
	v_mul_f32_e32 v22, v19, v22
	v_fma_f32 v22, v19, v22, v19
	v_mul_f32_e32 v22, 0xc0135761, v22
	v_exp_f32_e32 v23, v22
	v_mul_f32_e32 v22, 0x3d372713, v12
	v_mul_f32_e32 v22, v12, v22
	v_fma_f32 v22, v12, v22, v12
	v_mul_f32_e32 v22, 0xc0135761, v22
	v_exp_f32_e32 v24, v22
	v_rcp_f32_e32 v22, v0
	v_add_f32_e32 v0, 1.0, v23
	v_rcp_f32_e32 v23, v0
	v_add_f32_e32 v0, 1.0, v24
	v_mul_f32_e32 v24, 0x3d372713, v14
	v_rcp_f32_e32 v34, v0
	v_mul_f32_e32 v0, 0x3d372713, v13
	v_mul_f32_e32 v24, v14, v24
	v_mul_f32_e32 v25, 0x3d372713, v15
	v_mul_f32_e32 v0, v13, v0
	v_fma_f32 v24, v14, v24, v14
	v_mul_f32_e32 v25, v15, v25
	v_fma_f32 v0, v13, v0, v13
	v_mul_f32_e32 v24, 0xc0135761, v24
	v_fma_f32 v25, v15, v25, v15
	v_mul_f32_e32 v0, 0xc0135761, v0
	v_exp_f32_e32 v24, v24
	v_mul_f32_e32 v25, 0xc0135761, v25
	v_exp_f32_e32 v0, v0
	v_exp_f32_e32 v25, v25
	v_add_f32_e32 v24, 1.0, v24
	v_rcp_f32_e32 v36, v24
	v_add_f32_e32 v0, 1.0, v0
	v_add_f32_e32 v24, 1.0, v25
	v_rcp_f32_e32 v37, v24
	v_rcp_f32_e32 v35, v0
	v_pk_mul_f32 v[26:27], v[18:19], v[22:23]
	v_pk_mul_f32 v[24:25], v[16:17], v[20:21]
	v_pk_mul_f32 v[22:23], v[14:15], v[36:37]
	v_pk_mul_f32 v[20:21], v[12:13], v[34:35]
	s_branch .LBB0_344
